# attnprep: 10 heads batched per row (loads hoisted, interleaved bpermute reductions); s5 relayout rewritten with scalar row math and 9 loads in flight; attention K/V staging loads batched
# speedup vs baseline: 1.0192x; 1.0192x over previous
; __device__ __forceinline__ int opaque_tid() { int t = threadIdx.x; asm volatile("" : "+v"(t)); return t; }
; __device__ __forceinline__ void s5relayout_item(const Params& p, int item) {
;   int tid = opaque_tid(), wave = tid >> 6, lane = tid & 63;
;   const u16* ZA = (const u16*)(p.ws + O_ZA);
;   u16* UCS = (u16*)(p.ws + O_UCS);
;   int g = lane >> 1, half = lane & 1;
; #pragma unroll
;   for (int i = 0; i < 9; i++) {
;     int row = item * 72 + wave * 9 + i;
;     int b, j, tau;
;     if (row < TL) { b = row >> 11; int t = row & 2047; j = 8 + (t >> 5); tau = t & 31; }
;     else { int r = row - TL; b = r >> 8; int t = r & 255; j = t >> 5; tau = t & 31; }
;     u32x4 v = *(const u32x4*)(ZA + (size_t)row * 1280 + lane * 8);
;     *(u32x4*)(UCS + ((size_t)(g * 768 + b * 72 + j)) * 768 + tau * 16 + half * 8) = v;
;   }
; }
.LBB0_304:
	s_load_dwordx2 s[4:5], s[50:51], 0x150
	v_lshrrev_b32_e32 v2, 6, v228
	v_and_b32_e32 v3, 63, v228
	v_lshlrev_b32_e32 v4, 4, v3
	v_lshrrev_b32_e32 v5, 1, v3
	v_and_b32_e32 v6, 1, v3
	v_mul_u32_u24_e32 v5, 0x120000, v5
	v_lshl_or_b32 v5, v6, 4, v5
	v_readfirstlane_b32 s9, v2
	s_mul_i32 s9, s9, 9
	s_waitcnt lgkmcnt(0)
	s_add_u32 s10, s4, 0xa10c000
	s_addc_u32 s11, s5, 0
	s_add_u32 s12, s4, 0x4800000
	s_addc_u32 s13, s5, 0
.Lrl_item:
	s_mul_i32 s6, s8, 0x48
	s_add_i32 s6, s6, s9
	s_add_i32 s7, s6, 0
	s_mul_i32 s14, s7, 0xa00
	s_add_u32 s16, s10, s14
	s_addc_u32 s17, s11, 0
	global_load_dwordx4 v[12:15], v4, s[16:17]
	s_add_i32 s7, s6, 1
	s_mul_i32 s14, s7, 0xa00
	s_add_u32 s16, s10, s14
	s_addc_u32 s17, s11, 0
	global_load_dwordx4 v[16:19], v4, s[16:17]
	s_add_i32 s7, s6, 2
	s_mul_i32 s14, s7, 0xa00
	s_add_u32 s16, s10, s14
	s_addc_u32 s17, s11, 0
	global_load_dwordx4 v[20:23], v4, s[16:17]
	s_add_i32 s7, s6, 3
	s_mul_i32 s14, s7, 0xa00
	s_add_u32 s16, s10, s14
	s_addc_u32 s17, s11, 0
	global_load_dwordx4 v[24:27], v4, s[16:17]
	s_add_i32 s7, s6, 4
	s_mul_i32 s14, s7, 0xa00
	s_add_u32 s16, s10, s14
	s_addc_u32 s17, s11, 0
	global_load_dwordx4 v[28:31], v4, s[16:17]
	s_add_i32 s7, s6, 5
	s_mul_i32 s14, s7, 0xa00
	s_add_u32 s16, s10, s14
	s_addc_u32 s17, s11, 0
	global_load_dwordx4 v[32:35], v4, s[16:17]
	s_add_i32 s7, s6, 6
	s_mul_i32 s14, s7, 0xa00
	s_add_u32 s16, s10, s14
	s_addc_u32 s17, s11, 0
	global_load_dwordx4 v[36:39], v4, s[16:17]
	s_add_i32 s7, s6, 7
	s_mul_i32 s14, s7, 0xa00
	s_add_u32 s16, s10, s14
	s_addc_u32 s17, s11, 0
	global_load_dwordx4 v[40:43], v4, s[16:17]
	s_add_i32 s7, s6, 8
	s_mul_i32 s14, s7, 0xa00
	s_add_u32 s16, s10, s14
	s_addc_u32 s17, s11, 0
	global_load_dwordx4 v[44:47], v4, s[16:17]
	s_add_i32 s7, s6, 0
	s_lshr_b32 s14, s7, 11
	s_bfe_u32 s15, s7, 0x60005
	s_add_i32 s15, s15, 8
	s_sub_i32 s18, s7, 0x4000
	s_lshr_b32 s19, s18, 8
	s_bfe_u32 s18, s18, 0x30005
	s_cmp_lt_u32 s7, 0x4000
	s_cselect_b32 s14, s14, s19
	s_cselect_b32 s15, s15, s18
	s_mul_i32 s14, s14, 0x48
	s_add_i32 s14, s14, s15
	s_mul_i32 s14, s14, 0x600
	s_and_b32 s15, s7, 31
	s_lshl_b32 s15, s15, 5
	s_add_i32 s14, s14, s15
	s_add_u32 s16, s12, s14
	s_addc_u32 s17, s13, 0
	s_waitcnt vmcnt(8)
	global_store_dwordx4 v5, v[12:15], s[16:17]
	s_add_i32 s7, s6, 1
	s_lshr_b32 s14, s7, 11
	s_bfe_u32 s15, s7, 0x60005
	s_add_i32 s15, s15, 8
	s_sub_i32 s18, s7, 0x4000
	s_lshr_b32 s19, s18, 8
	s_bfe_u32 s18, s18, 0x30005
	s_cmp_lt_u32 s7, 0x4000
	s_cselect_b32 s14, s14, s19
	s_cselect_b32 s15, s15, s18
	s_mul_i32 s14, s14, 0x48
	s_add_i32 s14, s14, s15
	s_mul_i32 s14, s14, 0x600
	s_and_b32 s15, s7, 31
	s_lshl_b32 s15, s15, 5
	s_add_i32 s14, s14, s15
	s_add_u32 s16, s12, s14
	s_addc_u32 s17, s13, 0
	s_waitcnt vmcnt(8)
	global_store_dwordx4 v5, v[16:19], s[16:17]
	s_add_i32 s7, s6, 2
	s_lshr_b32 s14, s7, 11
	s_bfe_u32 s15, s7, 0x60005
	s_add_i32 s15, s15, 8
	s_sub_i32 s18, s7, 0x4000
	s_lshr_b32 s19, s18, 8
	s_bfe_u32 s18, s18, 0x30005
	s_cmp_lt_u32 s7, 0x4000
	s_cselect_b32 s14, s14, s19
	s_cselect_b32 s15, s15, s18
	s_mul_i32 s14, s14, 0x48
	s_add_i32 s14, s14, s15
	s_mul_i32 s14, s14, 0x600
	s_and_b32 s15, s7, 31
	s_lshl_b32 s15, s15, 5
	s_add_i32 s14, s14, s15
	s_add_u32 s16, s12, s14
	s_addc_u32 s17, s13, 0
	s_waitcnt vmcnt(8)
	global_store_dwordx4 v5, v[20:23], s[16:17]
	s_add_i32 s7, s6, 3
	s_lshr_b32 s14, s7, 11
	s_bfe_u32 s15, s7, 0x60005
	s_add_i32 s15, s15, 8
	s_sub_i32 s18, s7, 0x4000
	s_lshr_b32 s19, s18, 8
	s_bfe_u32 s18, s18, 0x30005
	s_cmp_lt_u32 s7, 0x4000
	s_cselect_b32 s14, s14, s19
	s_cselect_b32 s15, s15, s18
	s_mul_i32 s14, s14, 0x48
	s_add_i32 s14, s14, s15
	s_mul_i32 s14, s14, 0x600
	s_and_b32 s15, s7, 31
	s_lshl_b32 s15, s15, 5
	s_add_i32 s14, s14, s15
	s_add_u32 s16, s12, s14
	s_addc_u32 s17, s13, 0
	s_waitcnt vmcnt(8)
	global_store_dwordx4 v5, v[24:27], s[16:17]
	s_add_i32 s7, s6, 4
	s_lshr_b32 s14, s7, 11
	s_bfe_u32 s15, s7, 0x60005
	s_add_i32 s15, s15, 8
	s_sub_i32 s18, s7, 0x4000
	s_lshr_b32 s19, s18, 8
	s_bfe_u32 s18, s18, 0x30005
	s_cmp_lt_u32 s7, 0x4000
	s_cselect_b32 s14, s14, s19
	s_cselect_b32 s15, s15, s18
	s_mul_i32 s14, s14, 0x48
	s_add_i32 s14, s14, s15
	s_mul_i32 s14, s14, 0x600
	s_and_b32 s15, s7, 31
	s_lshl_b32 s15, s15, 5
	s_add_i32 s14, s14, s15
	s_add_u32 s16, s12, s14
	s_addc_u32 s17, s13, 0
	s_waitcnt vmcnt(8)
	global_store_dwordx4 v5, v[28:31], s[16:17]
	s_add_i32 s7, s6, 5
	s_lshr_b32 s14, s7, 11
	s_bfe_u32 s15, s7, 0x60005
	s_add_i32 s15, s15, 8
	s_sub_i32 s18, s7, 0x4000
	s_lshr_b32 s19, s18, 8
	s_bfe_u32 s18, s18, 0x30005
	s_cmp_lt_u32 s7, 0x4000
	s_cselect_b32 s14, s14, s19
	s_cselect_b32 s15, s15, s18
	s_mul_i32 s14, s14, 0x48
	s_add_i32 s14, s14, s15
	s_mul_i32 s14, s14, 0x600
	s_and_b32 s15, s7, 31
	s_lshl_b32 s15, s15, 5
	s_add_i32 s14, s14, s15
	s_add_u32 s16, s12, s14
	s_addc_u32 s17, s13, 0
	s_waitcnt vmcnt(8)
	global_store_dwordx4 v5, v[32:35], s[16:17]
	s_add_i32 s7, s6, 6
	s_lshr_b32 s14, s7, 11
	s_bfe_u32 s15, s7, 0x60005
	s_add_i32 s15, s15, 8
	s_sub_i32 s18, s7, 0x4000
	s_lshr_b32 s19, s18, 8
	s_bfe_u32 s18, s18, 0x30005
	s_cmp_lt_u32 s7, 0x4000
	s_cselect_b32 s14, s14, s19
	s_cselect_b32 s15, s15, s18
	s_mul_i32 s14, s14, 0x48
	s_add_i32 s14, s14, s15
	s_mul_i32 s14, s14, 0x600
	s_and_b32 s15, s7, 31
	s_lshl_b32 s15, s15, 5
	s_add_i32 s14, s14, s15
	s_add_u32 s16, s12, s14
	s_addc_u32 s17, s13, 0
	s_waitcnt vmcnt(8)
	global_store_dwordx4 v5, v[36:39], s[16:17]
	s_add_i32 s7, s6, 7
	s_lshr_b32 s14, s7, 11
	s_bfe_u32 s15, s7, 0x60005
	s_add_i32 s15, s15, 8
	s_sub_i32 s18, s7, 0x4000
	s_lshr_b32 s19, s18, 8
	s_bfe_u32 s18, s18, 0x30005
	s_cmp_lt_u32 s7, 0x4000
	s_cselect_b32 s14, s14, s19
	s_cselect_b32 s15, s15, s18
	s_mul_i32 s14, s14, 0x48
	s_add_i32 s14, s14, s15
	s_mul_i32 s14, s14, 0x600
	s_and_b32 s15, s7, 31
	s_lshl_b32 s15, s15, 5
	s_add_i32 s14, s14, s15
	s_add_u32 s16, s12, s14
	s_addc_u32 s17, s13, 0
	s_waitcnt vmcnt(8)
	global_store_dwordx4 v5, v[40:43], s[16:17]
	s_add_i32 s7, s6, 8
	s_lshr_b32 s14, s7, 11
	s_bfe_u32 s15, s7, 0x60005
	s_add_i32 s15, s15, 8
	s_sub_i32 s18, s7, 0x4000
	s_lshr_b32 s19, s18, 8
	s_bfe_u32 s18, s18, 0x30005
	s_cmp_lt_u32 s7, 0x4000
	s_cselect_b32 s14, s14, s19
	s_cselect_b32 s15, s15, s18
	s_mul_i32 s14, s14, 0x48
	s_add_i32 s14, s14, s15
	s_mul_i32 s14, s14, 0x600
	s_and_b32 s15, s7, 31
	s_lshl_b32 s15, s15, 5
	s_add_i32 s14, s14, s15
	s_add_u32 s16, s12, s14
	s_addc_u32 s17, s13, 0
	s_waitcnt vmcnt(8)
	global_store_dwordx4 v5, v[44:47], s[16:17]
	v_readlane_b32 s14, v254, 42
	s_add_i32 s8, s8, s14
	s_cmpk_lt_i32 s8, 0x100
	s_cbranch_scc1 .Lrl_item
	v_readlane_b32 s4, v254, 34
	v_readlane_b32 s5, v254, 0
	s_branch .LBB0_422

; __device__ __forceinline__ float bf2f(u16 h) { return __uint_as_float(((unsigned)h) << 16); }
; __device__ __forceinline__ void attnprep_item(const Params& p, int layer, int item) {
;     ...
;     for (int h = 0; h < 10; h++) {
;       float v = bf2f(ZA[(size_t)row * 1280 + 512 + h * 64 + lane]);
;       float ss = wave_sum(v * v);
;       float nv = v * rsqrtf(ss * (1.0f / 64.0f) + EPS) * (h < 8 ? qg : kg);
;       float pv = __shfl_xor(nv, 1);
.LBB0_424:
	s_or_b64 exec, exec, s[16:17]
	s_movk_i32 s8, 0xa00
	v_mad_i64_i32 v[10:11], s[8:9], v14, s8, v[4:5]
	global_load_ushort v40, v[10:11], off
	global_load_ushort v41, v[10:11], off offset:128
	global_load_ushort v42, v[10:11], off offset:256
	global_load_ushort v43, v[10:11], off offset:384
	global_load_ushort v44, v[10:11], off offset:512
	global_load_ushort v45, v[10:11], off offset:640
	global_load_ushort v46, v[10:11], off offset:768
	global_load_ushort v47, v[10:11], off offset:896
	global_load_ushort v48, v[10:11], off offset:1024
	global_load_ushort v49, v[10:11], off offset:1152
	v_ashrrev_i32_e32 v15, 31, v14
	v_lshlrev_b64 v[12:13], 8, v[14:15]
	v_lshlrev_b64 v[14:15], 10, v[14:15]
	v_lshl_add_u64 v[14:15], v[6:7], 0, v[14:15]
	v_lshl_add_u64 v[12:13], v[2:3], 0, v[12:13]
	v_lshl_add_u64 v[12:13], v[12:13], 0, v[160:161]
	s_mov_b32 s8, 0x1ca0c000
	v_add_co_u32_e64 v12, s[8:9], s8, v12
	s_nop 1
	v_addc_co_u32_e64 v13, s[8:9], 0, v13, s[8:9]
	s_add_i32 s20, s20, 1
	s_cmp_lg_u32 s20, 9
	s_waitcnt vmcnt(0) lgkmcnt(0)
	v_lshlrev_b32_e32 v40, 16, v40
	v_lshlrev_b32_e32 v41, 16, v41
	v_lshlrev_b32_e32 v42, 16, v42
	v_lshlrev_b32_e32 v43, 16, v43
	v_lshlrev_b32_e32 v44, 16, v44
	v_lshlrev_b32_e32 v45, 16, v45
	v_lshlrev_b32_e32 v46, 16, v46
	v_lshlrev_b32_e32 v47, 16, v47
	v_lshlrev_b32_e32 v48, 16, v48
	v_lshlrev_b32_e32 v49, 16, v49
	v_mul_f32_e32 v50, v40, v40
	v_mul_f32_e32 v51, v41, v41
	v_mul_f32_e32 v52, v42, v42
	v_mul_f32_e32 v53, v43, v43
	v_mul_f32_e32 v54, v44, v44
	v_mul_f32_e32 v55, v45, v45
	v_mul_f32_e32 v56, v46, v46
	v_mul_f32_e32 v57, v47, v47
	v_mul_f32_e32 v58, v48, v48
	v_mul_f32_e32 v59, v49, v49
	ds_bpermute_b32 v50, v19, v50
	ds_bpermute_b32 v51, v19, v51
	ds_bpermute_b32 v52, v19, v52
	ds_bpermute_b32 v53, v19, v53
	ds_bpermute_b32 v54, v19, v54
	ds_bpermute_b32 v55, v19, v55
	ds_bpermute_b32 v56, v19, v56
	ds_bpermute_b32 v57, v19, v57
	ds_bpermute_b32 v58, v19, v58
	ds_bpermute_b32 v59, v19, v59
	s_waitcnt lgkmcnt(0)
	v_fmac_f32_e32 v50, v40, v40
	v_fmac_f32_e32 v51, v41, v41
	v_fmac_f32_e32 v52, v42, v42
	v_fmac_f32_e32 v53, v43, v43
	v_fmac_f32_e32 v54, v44, v44
	v_fmac_f32_e32 v55, v45, v45
	v_fmac_f32_e32 v56, v46, v46
	v_fmac_f32_e32 v57, v47, v47
	v_fmac_f32_e32 v58, v48, v48
	v_fmac_f32_e32 v59, v49, v49
	ds_bpermute_b32 v60, v20, v50
	ds_bpermute_b32 v61, v20, v51
	ds_bpermute_b32 v62, v20, v52
	ds_bpermute_b32 v63, v20, v53
	ds_bpermute_b32 v64, v20, v54
	ds_bpermute_b32 v65, v20, v55
	ds_bpermute_b32 v66, v20, v56
	ds_bpermute_b32 v67, v20, v57
	ds_bpermute_b32 v68, v20, v58
	ds_bpermute_b32 v69, v20, v59
	s_waitcnt lgkmcnt(0)
	v_add_f32_e32 v50, v50, v60
	v_add_f32_e32 v51, v51, v61
	v_add_f32_e32 v52, v52, v62
	v_add_f32_e32 v53, v53, v63
	v_add_f32_e32 v54, v54, v64
	v_add_f32_e32 v55, v55, v65
	v_add_f32_e32 v56, v56, v66
	v_add_f32_e32 v57, v57, v67
	v_add_f32_e32 v58, v58, v68
	v_add_f32_e32 v59, v59, v69
	ds_bpermute_b32 v60, v21, v50
	ds_bpermute_b32 v61, v21, v51
	ds_bpermute_b32 v62, v21, v52
	ds_bpermute_b32 v63, v21, v53
	ds_bpermute_b32 v64, v21, v54
	ds_bpermute_b32 v65, v21, v55
	ds_bpermute_b32 v66, v21, v56
	ds_bpermute_b32 v67, v21, v57
	ds_bpermute_b32 v68, v21, v58
	ds_bpermute_b32 v69, v21, v59
	s_waitcnt lgkmcnt(0)
	v_add_f32_e32 v50, v50, v60
	v_add_f32_e32 v51, v51, v61
	v_add_f32_e32 v52, v52, v62
	v_add_f32_e32 v53, v53, v63
	v_add_f32_e32 v54, v54, v64
	v_add_f32_e32 v55, v55, v65
	v_add_f32_e32 v56, v56, v66
	v_add_f32_e32 v57, v57, v67
	v_add_f32_e32 v58, v58, v68
	v_add_f32_e32 v59, v59, v69
	ds_bpermute_b32 v60, v22, v50
	ds_bpermute_b32 v61, v22, v51
	ds_bpermute_b32 v62, v22, v52
	ds_bpermute_b32 v63, v22, v53
	ds_bpermute_b32 v64, v22, v54
	ds_bpermute_b32 v65, v22, v55
	ds_bpermute_b32 v66, v22, v56
	ds_bpermute_b32 v67, v22, v57
	ds_bpermute_b32 v68, v22, v58
	ds_bpermute_b32 v69, v22, v59
	s_waitcnt lgkmcnt(0)
	v_add_f32_e32 v50, v50, v60
	v_add_f32_e32 v51, v51, v61
	v_add_f32_e32 v52, v52, v62
	v_add_f32_e32 v53, v53, v63
	v_add_f32_e32 v54, v54, v64
	v_add_f32_e32 v55, v55, v65
	v_add_f32_e32 v56, v56, v66
	v_add_f32_e32 v57, v57, v67
	v_add_f32_e32 v58, v58, v68
	v_add_f32_e32 v59, v59, v69
	ds_bpermute_b32 v60, v23, v50
	ds_bpermute_b32 v61, v23, v51
	ds_bpermute_b32 v62, v23, v52
	ds_bpermute_b32 v63, v23, v53
	ds_bpermute_b32 v64, v23, v54
	ds_bpermute_b32 v65, v23, v55
	ds_bpermute_b32 v66, v23, v56
	ds_bpermute_b32 v67, v23, v57
	ds_bpermute_b32 v68, v23, v58
	ds_bpermute_b32 v69, v23, v59
	s_waitcnt lgkmcnt(0)
	v_add_f32_e32 v50, v50, v60
	v_add_f32_e32 v51, v51, v61
	v_add_f32_e32 v52, v52, v62
	v_add_f32_e32 v53, v53, v63
	v_add_f32_e32 v54, v54, v64
	v_add_f32_e32 v55, v55, v65
	v_add_f32_e32 v56, v56, v66
	v_add_f32_e32 v57, v57, v67
	v_add_f32_e32 v58, v58, v68
	v_add_f32_e32 v59, v59, v69
	ds_bpermute_b32 v60, v24, v50
	ds_bpermute_b32 v61, v24, v51
	ds_bpermute_b32 v62, v24, v52
	ds_bpermute_b32 v63, v24, v53
	ds_bpermute_b32 v64, v24, v54
	ds_bpermute_b32 v65, v24, v55
	ds_bpermute_b32 v66, v24, v56
	ds_bpermute_b32 v67, v24, v57
	ds_bpermute_b32 v68, v24, v58
	ds_bpermute_b32 v69, v24, v59
	s_waitcnt lgkmcnt(0)
; __device__ __forceinline__ u16 f2bf(float f) { unsigned r; asm("v_cvt_pk_bf16_f32 %0, %1, %1" : "=v"(r) : "v"(f)); return (u16)r; }
; __device__ __forceinline__ void attnprep_item(const Params& p, int layer, int item) {
;     ...
;       float ss = wave_sum(v * v);
;       float nv = v * rsqrtf(ss * (1.0f / 64.0f) + EPS) * (h < 8 ? qg : kg);
;       float pv = __shfl_xor(nv, 1);
;       float o = (lane & 1) ? (pv * sn + nv * cs) : (nv * cs - pv * sn);
;       if (h < 8) QR[(size_t)row * 512 + h * 64 + lane] = f2bf(o);
;       else KR[(size_t)row * 128 + (h - 8) * 64 + lane] = f2bf(o);
;     }
	v_add_f32_e32 v50, v50, v60
	v_add_f32_e32 v51, v51, v61
	v_add_f32_e32 v52, v52, v62
	v_add_f32_e32 v53, v53, v63
	v_add_f32_e32 v54, v54, v64
	v_add_f32_e32 v55, v55, v65
	v_add_f32_e32 v56, v56, v66
	v_add_f32_e32 v57, v57, v67
	v_add_f32_e32 v58, v58, v68
	v_add_f32_e32 v59, v59, v69
	v_fmamk_f32 v50, v50, 0x3c800000, v229
	v_fmamk_f32 v51, v51, 0x3c800000, v229
	v_fmamk_f32 v52, v52, 0x3c800000, v229
	v_fmamk_f32 v53, v53, 0x3c800000, v229
	v_fmamk_f32 v54, v54, 0x3c800000, v229
	v_fmamk_f32 v55, v55, 0x3c800000, v229
	v_fmamk_f32 v56, v56, 0x3c800000, v229
	v_fmamk_f32 v57, v57, 0x3c800000, v229
	v_fmamk_f32 v58, v58, 0x3c800000, v229
	v_fmamk_f32 v59, v59, 0x3c800000, v229
	v_cmp_gt_f32_e64 s[8:9], s89, v50
	v_mul_f32_e32 v60, 0x4b800000, v50
	s_nop 0
	v_cndmask_b32_e64 v50, v50, v60, s[8:9]
	v_rsq_f32_e32 v50, v50
	s_nop 0
	v_mul_f32_e32 v60, 0x45800000, v50
	v_cndmask_b32_e64 v50, v50, v60, s[8:9]
	v_mul_f32_e32 v40, v50, v40
	v_mul_f32_e32 v40, v16, v40
	v_cmp_gt_f32_e64 s[8:9], s89, v51
	v_mul_f32_e32 v61, 0x4b800000, v51
	s_nop 0
	v_cndmask_b32_e64 v51, v51, v61, s[8:9]
	v_rsq_f32_e32 v51, v51
	s_nop 0
	v_mul_f32_e32 v61, 0x45800000, v51
	v_cndmask_b32_e64 v51, v51, v61, s[8:9]
	v_mul_f32_e32 v41, v51, v41
	v_mul_f32_e32 v41, v16, v41
	v_cmp_gt_f32_e64 s[8:9], s89, v52
	v_mul_f32_e32 v62, 0x4b800000, v52
	s_nop 0
	v_cndmask_b32_e64 v52, v52, v62, s[8:9]
	v_rsq_f32_e32 v52, v52
	s_nop 0
	v_mul_f32_e32 v62, 0x45800000, v52
	v_cndmask_b32_e64 v52, v52, v62, s[8:9]
	v_mul_f32_e32 v42, v52, v42
	v_mul_f32_e32 v42, v16, v42
	v_cmp_gt_f32_e64 s[8:9], s89, v53
	v_mul_f32_e32 v63, 0x4b800000, v53
	s_nop 0
	v_cndmask_b32_e64 v53, v53, v63, s[8:9]
	v_rsq_f32_e32 v53, v53
	s_nop 0
	v_mul_f32_e32 v63, 0x45800000, v53
	v_cndmask_b32_e64 v53, v53, v63, s[8:9]
	v_mul_f32_e32 v43, v53, v43
	v_mul_f32_e32 v43, v16, v43
	v_cmp_gt_f32_e64 s[8:9], s89, v54
	v_mul_f32_e32 v64, 0x4b800000, v54
	s_nop 0
	v_cndmask_b32_e64 v54, v54, v64, s[8:9]
	v_rsq_f32_e32 v54, v54
	s_nop 0
	v_mul_f32_e32 v64, 0x45800000, v54
	v_cndmask_b32_e64 v54, v54, v64, s[8:9]
	v_mul_f32_e32 v44, v54, v44
	v_mul_f32_e32 v44, v16, v44
	v_cmp_gt_f32_e64 s[8:9], s89, v55
	v_mul_f32_e32 v65, 0x4b800000, v55
	s_nop 0
	v_cndmask_b32_e64 v55, v55, v65, s[8:9]
	v_rsq_f32_e32 v55, v55
	s_nop 0
	v_mul_f32_e32 v65, 0x45800000, v55
	v_cndmask_b32_e64 v55, v55, v65, s[8:9]
	v_mul_f32_e32 v45, v55, v45
	v_mul_f32_e32 v45, v16, v45
	v_cmp_gt_f32_e64 s[8:9], s89, v56
	v_mul_f32_e32 v66, 0x4b800000, v56
	s_nop 0
	v_cndmask_b32_e64 v56, v56, v66, s[8:9]
	v_rsq_f32_e32 v56, v56
	s_nop 0
	v_mul_f32_e32 v66, 0x45800000, v56
	v_cndmask_b32_e64 v56, v56, v66, s[8:9]
	v_mul_f32_e32 v46, v56, v46
	v_mul_f32_e32 v46, v16, v46
	v_cmp_gt_f32_e64 s[8:9], s89, v57
	v_mul_f32_e32 v67, 0x4b800000, v57
	s_nop 0
	v_cndmask_b32_e64 v57, v57, v67, s[8:9]
	v_rsq_f32_e32 v57, v57
	s_nop 0
	v_mul_f32_e32 v67, 0x45800000, v57
	v_cndmask_b32_e64 v57, v57, v67, s[8:9]
	v_mul_f32_e32 v47, v57, v47
	v_mul_f32_e32 v47, v16, v47
	v_cmp_gt_f32_e64 s[8:9], s89, v58
	v_mul_f32_e32 v68, 0x4b800000, v58
	s_nop 0
	v_cndmask_b32_e64 v58, v58, v68, s[8:9]
	v_rsq_f32_e32 v58, v58
	s_nop 0
	v_mul_f32_e32 v68, 0x45800000, v58
	v_cndmask_b32_e64 v58, v58, v68, s[8:9]
	v_mul_f32_e32 v48, v58, v48
	v_mul_f32_e32 v48, v17, v48
	v_cmp_gt_f32_e64 s[8:9], s89, v59
	v_mul_f32_e32 v69, 0x4b800000, v59
	s_nop 0
	v_cndmask_b32_e64 v59, v59, v69, s[8:9]
	v_rsq_f32_e32 v59, v59
	s_nop 0
	v_mul_f32_e32 v69, 0x45800000, v59
	v_cndmask_b32_e64 v59, v59, v69, s[8:9]
	v_mul_f32_e32 v49, v59, v49
	v_mul_f32_e32 v49, v17, v49
	ds_bpermute_b32 v60, v24, v40
	ds_bpermute_b32 v61, v24, v41
	ds_bpermute_b32 v62, v24, v42
	ds_bpermute_b32 v63, v24, v43
	ds_bpermute_b32 v64, v24, v44
	ds_bpermute_b32 v65, v24, v45
	ds_bpermute_b32 v66, v24, v46
	ds_bpermute_b32 v67, v24, v47
	ds_bpermute_b32 v68, v24, v48
	ds_bpermute_b32 v69, v24, v49
	s_waitcnt lgkmcnt(0)
	v_mul_f32_e32 v60, v25, v60
	v_cndmask_b32_e64 v60, v60, -v60, vcc
	v_fmac_f32_e32 v60, v9, v40
	v_cvt_pk_bf16_f32 v40, v60, v60
	v_mul_f32_e32 v61, v25, v61
	v_cndmask_b32_e64 v61, v61, -v61, vcc
	v_fmac_f32_e32 v61, v9, v41
	v_cvt_pk_bf16_f32 v41, v61, v61
	v_mul_f32_e32 v62, v25, v62
	v_cndmask_b32_e64 v62, v62, -v62, vcc
	v_fmac_f32_e32 v62, v9, v42
	v_cvt_pk_bf16_f32 v42, v62, v62
	v_mul_f32_e32 v63, v25, v63
	v_cndmask_b32_e64 v63, v63, -v63, vcc
	v_fmac_f32_e32 v63, v9, v43
	v_cvt_pk_bf16_f32 v43, v63, v63
	v_mul_f32_e32 v64, v25, v64
	v_cndmask_b32_e64 v64, v64, -v64, vcc
	v_fmac_f32_e32 v64, v9, v44
	v_cvt_pk_bf16_f32 v44, v64, v64
	v_mul_f32_e32 v65, v25, v65
	v_cndmask_b32_e64 v65, v65, -v65, vcc
	v_fmac_f32_e32 v65, v9, v45
	v_cvt_pk_bf16_f32 v45, v65, v65
	v_mul_f32_e32 v66, v25, v66
	v_cndmask_b32_e64 v66, v66, -v66, vcc
	v_fmac_f32_e32 v66, v9, v46
	v_cvt_pk_bf16_f32 v46, v66, v66
	v_mul_f32_e32 v67, v25, v67
	v_cndmask_b32_e64 v67, v67, -v67, vcc
	v_fmac_f32_e32 v67, v9, v47
	v_cvt_pk_bf16_f32 v47, v67, v67
	v_mul_f32_e32 v68, v25, v68
	v_cndmask_b32_e64 v68, v68, -v68, vcc
	v_fmac_f32_e32 v68, v9, v48
	v_cvt_pk_bf16_f32 v48, v68, v68
	v_mul_f32_e32 v69, v25, v69
	v_cndmask_b32_e64 v69, v69, -v69, vcc
	v_fmac_f32_e32 v69, v9, v49
	v_cvt_pk_bf16_f32 v49, v69, v69
	global_store_short v[14:15], v40, off
	global_store_short v[14:15], v41, off offset:128
	global_store_short v[14:15], v42, off offset:256
	global_store_short v[14:15], v43, off offset:384
	global_store_short v[14:15], v44, off offset:512
	global_store_short v[14:15], v45, off offset:640
	global_store_short v[14:15], v46, off offset:768
	global_store_short v[14:15], v47, off offset:896
	global_store_short v[12:13], v48, off
	global_store_short v[12:13], v49, off offset:128
	s_cbranch_scc0 .LBB0_421

; __device__ __forceinline__ void attn_item(const Params& p, int layer, bool isctx, int item, unsigned char* smem) {
;     ...
;     __syncthreads();
; #pragma unroll
;     for (int i = 0; i < 2; i++) {
;       int e = tid + NT * i;
;       int r = e >> 3, cch = (e & 7) * 8;
;       *(uint4*)(Ks + r * 72 + cch) = *(const uint4*)(KR + (size_t)(krow0 + r) * 128 + kvh * 64 + cch);
;       int d = e >> 4, kc = (e & 15) * 8;
;       *(uint4*)(Vt + d * 136 + kc) = *(const uint4*)(VT + (size_t)(kvh * 64 + d) * TA + krow0 + kc);
;     }
;     __syncthreads();
; #pragma unroll
;     for (int k4 = 0; k4 < 4; k4++) {
;       f32x16 st;
; #pragma unroll
;       for (int r = 0; r < 16; r++) st[r] = 0.f;
; #pragma unroll
;       for (int ks = 0; ks < 4; ks++) {
;         bf16x8 kf = *(const bf16x8*)(Ks + (k4 * 32 + (lane & 31)) * 72 + ks * 16 + hh * 8);
;         st = __builtin_amdgcn_mfma_f32_32x32x16_bf16(kf, qf[ks], st, 0, 0, 0);
;       }
;       float pe[16];
; #pragma unroll
;       for (int r = 0; r < 16; r++) {
;         int kl = k4 * 32 + (r & 3) + 8 * (r >> 2) + 4 * hh;
;         float e = __expf(st[r] * 0.125f);
;         bool valid = (mtype * kl) <= mq;
;         e = valid ? e : 0.f;
;         pe[r] = e; rsum += e;
;       }
.LBB0_488:
	v_add_u32_e32 v32, s8, v82
	v_ashrrev_i32_e32 v33, 31, v32
	v_lshlrev_b64 v[32:33], 8, v[32:33]
	v_lshl_add_u64 v[32:33], v[68:69], 0, v[32:33]
	s_waitcnt lgkmcnt(0)
	s_barrier
	global_load_dwordx4 v[40:43], v[32:33], off
	s_ashr_i32 s9, s8, 31
	v_lshl_add_u64 v[36:37], s[8:9], 1, v[70:71]
	v_mul_lo_u32 v88, s19, v81
	v_mul_lo_u32 v87, s19, v67
	v_cmp_le_i32_e32 vcc, v87, v88
	v_lshl_add_u64 v[32:33], v[36:37], 0, v[74:75]
	global_load_dwordx4 v[44:47], v[32:33], off
	v_add_u32_e32 v32, s8, v83
	v_ashrrev_i32_e32 v33, 31, v32
	v_lshlrev_b64 v[32:33], 8, v[32:33]
	v_lshl_add_u64 v[32:33], v[68:69], 0, v[32:33]
	global_load_dwordx4 v[90:93], v[32:33], off
	v_lshl_add_u64 v[32:33], v[36:37], 0, v[78:79]
	global_load_dwordx4 v[32:35], v[32:33], off
	s_mul_i32 s8, s19, 5
	s_waitcnt vmcnt(3)
	ds_write_b128 v72, v[40:43]
	s_waitcnt vmcnt(2)
	ds_write_b128 v73, v[44:47]
	s_waitcnt vmcnt(1)
	ds_write_b128 v76, v[90:93]
	s_waitcnt vmcnt(0)
	ds_write_b128 v77, v[32:35]
	s_waitcnt lgkmcnt(0)
	s_barrier
	ds_read_b128 v[32:35], v84
	ds_read_b128 v[90:93], v84 offset:32
	s_waitcnt lgkmcnt(1)
	v_mfma_f32_32x32x16_bf16 v[32:47], v[32:35], v[56:59], 0
	s_waitcnt lgkmcnt(0)
	v_mfma_f32_32x32x16_bf16 v[32:47], v[90:93], v[48:51], v[32:47]
	ds_read_b128 v[90:93], v84 offset:64
	s_waitcnt lgkmcnt(0)
	v_mfma_f32_32x32x16_bf16 v[32:47], v[90:93], v[52:55], v[32:47]
	ds_read_b128 v[90:93], v84 offset:96
	s_waitcnt lgkmcnt(0)
	v_mfma_f32_32x32x16_bf16 v[32:47], v[90:93], v[60:63], v[32:47]
	s_nop 11
	v_mul_f32_e32 v32, 0x3e000000, v32
	v_mul_f32_e32 v32, 0x3fb8aa3b, v32
	v_exp_f32_e32 v32, v32
	s_nop 0
	v_cndmask_b32_e32 v89, 0, v32, vcc
	v_mul_f32_e32 v32, 0x3e000000, v33
	v_mul_f32_e32 v32, 0x3fb8aa3b, v32
	v_exp_f32_e32 v32, v32
	v_add_u32_e32 v33, s19, v87
	v_cmp_le_i32_e32 vcc, v33, v88
	v_add_u32_e32 v33, s19, v33
	s_nop 0
	v_cndmask_b32_e32 v87, 0, v32, vcc
	v_mul_f32_e32 v32, 0x3e000000, v34
	v_mul_f32_e32 v32, 0x3fb8aa3b, v32
	v_exp_f32_e32 v32, v32
	v_cmp_le_i32_e32 vcc, v33, v88
	v_add_u32_e32 v33, s19, v33
	s_nop 0
	v_cndmask_b32_e32 v90, 0, v32, vcc
	v_mul_f32_e32 v32, 0x3e000000, v35
	v_mul_f32_e32 v32, 0x3fb8aa3b, v32
	v_exp_f32_e32 v32, v32
	v_cmp_le_i32_e32 vcc, v33, v88
	v_add_u32_e32 v33, s8, v33
	s_nop 0
	v_cndmask_b32_e32 v91, 0, v32, vcc
	v_mul_f32_e32 v32, 0x3e000000, v36
	v_mul_f32_e32 v32, 0x3fb8aa3b, v32
	v_exp_f32_e32 v32, v32
	v_cmp_le_i32_e32 vcc, v33, v88
	v_add_u32_e32 v33, s19, v33
	s_nop 0
	v_cndmask_b32_e32 v92, 0, v32, vcc
	v_mul_f32_e32 v32, 0x3e000000, v37
	v_mul_f32_e32 v32, 0x3fb8aa3b, v32
	v_exp_f32_e32 v32, v32
	v_cmp_le_i32_e32 vcc, v33, v88
	v_add_u32_e32 v33, s19, v33
	s_nop 0
	v_cndmask_b32_e32 v93, 0, v32, vcc
	v_mul_f32_e32 v32, 0x3e000000, v38
	v_mul_f32_e32 v32, 0x3fb8aa3b, v32
	v_exp_f32_e32 v32, v32
	v_cmp_le_i32_e32 vcc, v33, v88
	v_add_u32_e32 v33, s19, v33
	v_cvt_pk_bf16_f32 v34, v92, v93
	s_nop 0
	v_cndmask_b32_e32 v94, 0, v32, vcc
	v_mul_f32_e32 v32, 0x3e000000, v39
	v_mul_f32_e32 v32, 0x3fb8aa3b, v32
	v_exp_f32_e32 v32, v32
	v_cmp_le_i32_e32 vcc, v33, v88
	v_add_u32_e32 v33, s8, v33
	s_nop 0
	v_cndmask_b32_e32 v95, 0, v32, vcc
	v_mul_f32_e32 v32, 0x3e000000, v40
	v_mul_f32_e32 v32, 0x3fb8aa3b, v32
	v_exp_f32_e32 v32, v32
	v_cmp_le_i32_e32 vcc, v33, v88
	v_add_u32_e32 v33, s19, v33
	v_cvt_pk_bf16_f32 v35, v94, v95
	s_nop 0
	v_cndmask_b32_e32 v40, 0, v32, vcc
	v_mul_f32_e32 v32, 0x3e000000, v41
	v_mul_f32_e32 v32, 0x3fb8aa3b, v32
	v_exp_f32_e32 v32, v32
	v_cmp_le_i32_e32 vcc, v33, v88
	v_add_u32_e32 v33, s19, v33
	s_nop 0
	v_cndmask_b32_e32 v41, 0, v32, vcc
	v_mul_f32_e32 v32, 0x3e000000, v42
	v_mul_f32_e32 v32, 0x3fb8aa3b, v32
	v_exp_f32_e32 v32, v32
	v_cmp_le_i32_e32 vcc, v33, v88
	v_add_u32_e32 v33, s19, v33
	v_cvt_pk_bf16_f32 v36, v40, v41
	s_nop 0
	v_cndmask_b32_e32 v42, 0, v32, vcc
	v_mul_f32_e32 v32, 0x3e000000, v43
	v_mul_f32_e32 v32, 0x3fb8aa3b, v32
	v_exp_f32_e32 v32, v32
	v_cmp_le_i32_e32 vcc, v33, v88
	v_add_u32_e32 v33, s8, v33
	s_nop 0
	v_cndmask_b32_e32 v43, 0, v32, vcc
	v_mul_f32_e32 v32, 0x3e000000, v44
	v_mul_f32_e32 v32, 0x3fb8aa3b, v32
	v_exp_f32_e32 v32, v32
	v_cmp_le_i32_e32 vcc, v33, v88
	v_add_u32_e32 v33, s19, v33
	v_cvt_pk_bf16_f32 v37, v42, v43
	s_nop 0
	v_cndmask_b32_e32 v44, 0, v32, vcc
	v_mul_f32_e32 v32, 0x3e000000, v45
	v_mul_f32_e32 v32, 0x3fb8aa3b, v32
	v_exp_f32_e32 v32, v32
	v_cmp_le_i32_e32 vcc, v33, v88
	v_add_u32_e32 v33, s19, v33
	v_add_u32_e32 v96, s19, v33
	v_cndmask_b32_e32 v45, 0, v32, vcc
	v_mul_f32_e32 v32, 0x3e000000, v46
	v_mul_f32_e32 v32, 0x3fb8aa3b, v32
	v_exp_f32_e32 v32, v32
	v_cmp_le_i32_e32 vcc, v33, v88
	v_cvt_pk_bf16_f32 v38, v44, v45
	v_cvt_pk_bf16_f32 v33, v90, v91
	s_nop 1
	v_cndmask_b32_e32 v46, 0, v32, vcc
	v_mul_f32_e32 v32, 0x3e000000, v47
	v_add_f32_e32 v47, v86, v89
	v_add_f32_e32 v47, v87, v47
	v_add_f32_e32 v47, v90, v47
	v_add_f32_e32 v47, v91, v47
	v_add_f32_e32 v47, v92, v47
	v_add_f32_e32 v47, v93, v47
	v_add_f32_e32 v47, v94, v47
	v_add_f32_e32 v47, v95, v47
	v_mul_f32_e32 v32, 0x3fb8aa3b, v32
	v_add_f32_e32 v40, v40, v47
	v_exp_f32_e32 v32, v32
	v_add_f32_e32 v40, v41, v40
	v_add_f32_e32 v40, v42, v40
	v_add_f32_e32 v40, v43, v40
	v_cmp_le_i32_e32 vcc, v96, v88
	v_add_f32_e32 v40, v44, v40
	v_add_f32_e32 v40, v45, v40
	v_cndmask_b32_e32 v97, 0, v32, vcc
	v_cvt_pk_bf16_f32 v32, v89, v87
	v_add_u32_e32 v87, 0x4800, v85
	v_cvt_pk_bf16_f32 v39, v46, v97
	v_add_f32_e32 v89, v46, v40
	ds_read2_b64 v[40:43], v87 offset1:2
	ds_read2_b64 v[44:47], v87 offset0:4 offset1:6
	v_add_u32_e32 v86, 0x6800, v85
	s_waitcnt lgkmcnt(1)
; __device__ __forceinline__ unsigned pack2(float a, float b) { unsigned r; asm("v_cvt_pk_bf16_f32 %0, %1, %2" : "=v"(r) : "v"(a), "v"(b)); return r; }
; __device__ __forceinline__ void attn_item(const Params& p, int layer, bool isctx, int item, unsigned char* smem) {
;     ...
; #pragma unroll
;     for (int k4 = 0; k4 < 4; k4++) {
;       f32x16 st;
; #pragma unroll
;       for (int r = 0; r < 16; r++) st[r] = 0.f;
; #pragma unroll
;       for (int ks = 0; ks < 4; ks++) {
;         bf16x8 kf = *(const bf16x8*)(Ks + (k4 * 32 + (lane & 31)) * 72 + ks * 16 + hh * 8);
;         st = __builtin_amdgcn_mfma_f32_32x32x16_bf16(kf, qf[ks], st, 0, 0, 0);
;       }
;       float pe[16];
; #pragma unroll
;       for (int r = 0; r < 16; r++) {
;         int kl = k4 * 32 + (r & 3) + 8 * (r >> 2) + 4 * hh;
;         float e = __expf(st[r] * 0.125f);
;         bool valid = (mtype * kl) <= mq;
;         e = valid ? e : 0.f;
;         pe[r] = e; rsum += e;
;       }
;       bf16x8 pb[2];
; #pragma unroll
;       for (int s = 0; s < 2; s++) {
;         union { bf16x8 v; unsigned w[4]; } cv;
; #pragma unroll
;         for (int q = 0; q < 4; q++) cv.w[q] = pack2(pe[8 * s + 2 * q], pe[8 * s + 2 * q + 1]);
;         pb[s] = cv.v;
;       }
; #pragma unroll
;       for (int mt = 0; mt < 2; mt++)
; #pragma unroll
;         for (int s = 0; s < 2; s++) {
;           const u16* vp = Vt + (mt * 32 + (lane & 31)) * 136 + k4 * 32 + 16 * s + 4 * hh;
;           union { bf16x8 v; uint2 h2[2]; } av;
;           av.h2[0] = *(const uint2*)vp;
;           av.h2[1] = *(const uint2*)(vp + 8);
;           oacc[mt] = __builtin_amdgcn_mfma_f32_32x32x16_bf16(av.v, pb[s], oacc[mt], 0, 0, 0);
;         }
	v_mfma_f32_32x32x16_bf16 v[16:31], v[40:43], v[32:35], v[16:31]
	ds_read2_b64 v[40:43], v86 offset0:64 offset1:66
	ds_read_b128 v[92:95], v84 offset:4640
	v_add_f32_e32 v90, v97, v89
	v_add_u32_e32 v89, s8, v96
	v_cmp_le_i32_e32 vcc, v89, v88
	s_waitcnt lgkmcnt(1)
	v_mfma_f32_32x32x16_bf16 v[0:15], v[40:43], v[32:35], v[0:15]
	ds_read2_b64 v[32:35], v86 offset0:68 offset1:70
	s_waitcnt lgkmcnt(0)
	v_mfma_f32_32x32x16_bf16 v[0:15], v[32:35], v[36:39], v[0:15]
	ds_read_b128 v[32:35], v84 offset:4608
	v_mfma_f32_32x32x16_bf16 v[16:31], v[44:47], v[36:39], v[16:31]
	s_waitcnt lgkmcnt(0)
	v_mfma_f32_32x32x16_bf16 v[32:47], v[32:35], v[56:59], 0
	v_mfma_f32_32x32x16_bf16 v[32:47], v[92:95], v[48:51], v[32:47]
	ds_read_b128 v[92:95], v84 offset:4672
	s_waitcnt lgkmcnt(0)
	v_mfma_f32_32x32x16_bf16 v[32:47], v[92:95], v[52:55], v[32:47]
	ds_read_b128 v[92:95], v84 offset:4704
	s_waitcnt lgkmcnt(0)
	v_mfma_f32_32x32x16_bf16 v[32:47], v[92:95], v[60:63], v[32:47]
	s_nop 11
	v_mul_f32_e32 v32, 0x3e000000, v32
	v_mul_f32_e32 v32, 0x3fb8aa3b, v32
	v_exp_f32_e32 v32, v32
	s_nop 0
	v_cndmask_b32_e32 v91, 0, v32, vcc
	v_mul_f32_e32 v32, 0x3e000000, v33
	v_mul_f32_e32 v32, 0x3fb8aa3b, v32
	v_exp_f32_e32 v32, v32
	v_add_u32_e32 v33, s19, v89
	v_cmp_le_i32_e32 vcc, v33, v88
	v_add_u32_e32 v33, s19, v33
	v_add_f32_e32 v90, v90, v91
	v_cndmask_b32_e32 v92, 0, v32, vcc
	v_mul_f32_e32 v32, 0x3e000000, v34
	v_mul_f32_e32 v32, 0x3fb8aa3b, v32
	v_exp_f32_e32 v32, v32
	v_cmp_le_i32_e32 vcc, v33, v88
	v_add_u32_e32 v33, s19, v33
	v_add_f32_e32 v90, v92, v90
	v_cndmask_b32_e32 v93, 0, v32, vcc
	v_mul_f32_e32 v32, 0x3e000000, v35
	v_mul_f32_e32 v32, 0x3fb8aa3b, v32
	v_exp_f32_e32 v32, v32
	v_cmp_le_i32_e32 vcc, v33, v88
	v_add_u32_e32 v33, s8, v33
	v_add_f32_e32 v90, v93, v90
	v_cndmask_b32_e32 v94, 0, v32, vcc
	v_mul_f32_e32 v32, 0x3e000000, v36
	v_mul_f32_e32 v32, 0x3fb8aa3b, v32
	v_exp_f32_e32 v32, v32
	v_cmp_le_i32_e32 vcc, v33, v88
	v_add_u32_e32 v33, s19, v33
	v_add_f32_e32 v90, v94, v90
	v_cndmask_b32_e32 v95, 0, v32, vcc
	v_mul_f32_e32 v32, 0x3e000000, v37
	v_mul_f32_e32 v32, 0x3fb8aa3b, v32
	v_exp_f32_e32 v32, v32
	v_cmp_le_i32_e32 vcc, v33, v88
	v_add_u32_e32 v33, s19, v33
	v_add_f32_e32 v90, v95, v90
	v_cndmask_b32_e32 v96, 0, v32, vcc
	v_mul_f32_e32 v32, 0x3e000000, v38
	v_mul_f32_e32 v32, 0x3fb8aa3b, v32
	v_exp_f32_e32 v32, v32
	v_cmp_le_i32_e32 vcc, v33, v88
	v_add_u32_e32 v33, s19, v33
	v_add_f32_e32 v90, v96, v90
	v_cndmask_b32_e32 v97, 0, v32, vcc
	v_mul_f32_e32 v32, 0x3e000000, v39
	v_mul_f32_e32 v32, 0x3fb8aa3b, v32
	v_exp_f32_e32 v32, v32
	v_cmp_le_i32_e32 vcc, v33, v88
	v_add_u32_e32 v33, s8, v33
	v_add_f32_e32 v90, v97, v90
	v_cndmask_b32_e32 v98, 0, v32, vcc
	v_mul_f32_e32 v32, 0x3e000000, v40
	v_mul_f32_e32 v32, 0x3fb8aa3b, v32
	v_exp_f32_e32 v32, v32
	v_cmp_le_i32_e32 vcc, v33, v88
	v_add_u32_e32 v33, s19, v33
	v_add_f32_e32 v90, v98, v90
	v_cndmask_b32_e32 v40, 0, v32, vcc
	v_mul_f32_e32 v32, 0x3e000000, v41
	v_mul_f32_e32 v32, 0x3fb8aa3b, v32
	v_exp_f32_e32 v32, v32
	v_cmp_le_i32_e32 vcc, v33, v88
	v_add_u32_e32 v33, s19, v33
	v_cvt_pk_bf16_f32 v34, v95, v96
	v_cvt_pk_bf16_f32 v35, v97, v98
	s_nop 0
	v_cndmask_b32_e32 v41, 0, v32, vcc
	v_mul_f32_e32 v32, 0x3e000000, v42
	v_mul_f32_e32 v32, 0x3fb8aa3b, v32
	v_exp_f32_e32 v32, v32
	v_cmp_le_i32_e32 vcc, v33, v88
	v_add_u32_e32 v33, s19, v33
	v_cvt_pk_bf16_f32 v36, v40, v41
	v_add_f32_e32 v40, v40, v90
	v_cndmask_b32_e32 v42, 0, v32, vcc
	v_mul_f32_e32 v32, 0x3e000000, v43
	v_mul_f32_e32 v32, 0x3fb8aa3b, v32
	v_exp_f32_e32 v32, v32
	v_cmp_le_i32_e32 vcc, v33, v88
	v_add_u32_e32 v33, s8, v33
	v_add_f32_e32 v40, v41, v40
	v_cndmask_b32_e32 v43, 0, v32, vcc
	v_mul_f32_e32 v32, 0x3e000000, v44
	v_mul_f32_e32 v32, 0x3fb8aa3b, v32
	v_exp_f32_e32 v32, v32
	v_cmp_le_i32_e32 vcc, v33, v88
	v_add_u32_e32 v33, s19, v33
	v_add_f32_e32 v40, v42, v40
	v_cndmask_b32_e32 v44, 0, v32, vcc
	v_mul_f32_e32 v32, 0x3e000000, v45
	v_mul_f32_e32 v32, 0x3fb8aa3b, v32
	v_exp_f32_e32 v32, v32
	v_cmp_le_i32_e32 vcc, v33, v88
	v_add_u32_e32 v33, s19, v33
	v_add_f32_e32 v40, v43, v40
	v_cndmask_b32_e32 v45, 0, v32, vcc
	v_mul_f32_e32 v32, 0x3e000000, v46
	v_mul_f32_e32 v32, 0x3fb8aa3b, v32
	v_exp_f32_e32 v32, v32
	v_cmp_le_i32_e32 vcc, v33, v88
	v_add_f32_e32 v40, v44, v40
	v_add_f32_e32 v40, v45, v40
	v_cndmask_b32_e32 v46, 0, v32, vcc
	v_cvt_pk_bf16_f32 v37, v42, v43
	v_cvt_pk_bf16_f32 v38, v44, v45
	v_add_f32_e32 v44, v46, v40
	ds_read2_b64 v[40:43], v87 offset0:8 offset1:10
	v_mul_f32_e32 v32, 0x3e000000, v47
	v_mul_f32_e32 v32, 0x3fb8aa3b, v32
	v_exp_f32_e32 v32, v32
	v_add_u32_e32 v89, s19, v33
	v_cmp_le_i32_e32 vcc, v89, v88
	v_cvt_pk_bf16_f32 v33, v93, v94
	v_add_u32_e32 v89, s8, v89
	s_nop 0
	v_cndmask_b32_e32 v47, 0, v32, vcc
	v_cvt_pk_bf16_f32 v32, v91, v92
	v_cvt_pk_bf16_f32 v39, v46, v47
	ds_read_b128 v[92:95], v84 offset:9248
	s_waitcnt lgkmcnt(1)
	v_mfma_f32_32x32x16_bf16 v[16:31], v[40:43], v[32:35], v[16:31]
	ds_read2_b64 v[40:43], v87 offset0:12 offset1:14
	v_add_f32_e32 v90, v47, v44
	v_cmp_le_i32_e32 vcc, v89, v88
	s_waitcnt lgkmcnt(0)
	v_mfma_f32_32x32x16_bf16 v[16:31], v[40:43], v[36:39], v[16:31]
	ds_read2_b64 v[40:43], v86 offset0:72 offset1:74
	s_waitcnt lgkmcnt(0)
	v_mfma_f32_32x32x16_bf16 v[0:15], v[40:43], v[32:35], v[0:15]
	ds_read2_b64 v[32:35], v86 offset0:76 offset1:78
	s_waitcnt lgkmcnt(0)
	v_mfma_f32_32x32x16_bf16 v[0:15], v[32:35], v[36:39], v[0:15]
	ds_read_b128 v[32:35], v84 offset:9216
	s_waitcnt lgkmcnt(0)
	v_mfma_f32_32x32x16_bf16 v[32:47], v[32:35], v[56:59], 0
	v_mfma_f32_32x32x16_bf16 v[32:47], v[92:95], v[48:51], v[32:47]
	ds_read_b128 v[92:95], v84 offset:9280
	s_waitcnt lgkmcnt(0)
; __device__ __forceinline__ unsigned pack2(float a, float b) { unsigned r; asm("v_cvt_pk_bf16_f32 %0, %1, %2" : "=v"(r) : "v"(a), "v"(b)); return r; }
; __device__ __forceinline__ void attn_item(const Params& p, int layer, bool isctx, int item, unsigned char* smem) {
;     ...
; #pragma unroll
;     for (int k4 = 0; k4 < 4; k4++) {
;       f32x16 st;
; #pragma unroll
;       for (int r = 0; r < 16; r++) st[r] = 0.f;
; #pragma unroll
;       for (int ks = 0; ks < 4; ks++) {
;         bf16x8 kf = *(const bf16x8*)(Ks + (k4 * 32 + (lane & 31)) * 72 + ks * 16 + hh * 8);
;         st = __builtin_amdgcn_mfma_f32_32x32x16_bf16(kf, qf[ks], st, 0, 0, 0);
;       }
;       float pe[16];
; #pragma unroll
;       for (int r = 0; r < 16; r++) {
;         int kl = k4 * 32 + (r & 3) + 8 * (r >> 2) + 4 * hh;
;         float e = __expf(st[r] * 0.125f);
;         bool valid = (mtype * kl) <= mq;
;         e = valid ? e : 0.f;
;         pe[r] = e; rsum += e;
;       }
;       bf16x8 pb[2];
; #pragma unroll
;       for (int s = 0; s < 2; s++) {
;         union { bf16x8 v; unsigned w[4]; } cv;
; #pragma unroll
;         for (int q = 0; q < 4; q++) cv.w[q] = pack2(pe[8 * s + 2 * q], pe[8 * s + 2 * q + 1]);
;         pb[s] = cv.v;
;       }
; #pragma unroll
;       for (int mt = 0; mt < 2; mt++)
; #pragma unroll
;         for (int s = 0; s < 2; s++) {
;           const u16* vp = Vt + (mt * 32 + (lane & 31)) * 136 + k4 * 32 + 16 * s + 4 * hh;
;           union { bf16x8 v; uint2 h2[2]; } av;
;           av.h2[0] = *(const uint2*)vp;
;           av.h2[1] = *(const uint2*)(vp + 8);
;           oacc[mt] = __builtin_amdgcn_mfma_f32_32x32x16_bf16(av.v, pb[s], oacc[mt], 0, 0, 0);
;         }
	v_mfma_f32_32x32x16_bf16 v[32:47], v[92:95], v[52:55], v[32:47]
	ds_read_b128 v[92:95], v84 offset:9312
	s_waitcnt lgkmcnt(0)
	v_mfma_f32_32x32x16_bf16 v[32:47], v[92:95], v[60:63], v[32:47]
	s_nop 11
	v_mul_f32_e32 v32, 0x3e000000, v32
	v_mul_f32_e32 v32, 0x3fb8aa3b, v32
	v_exp_f32_e32 v32, v32
	s_nop 0
	v_cndmask_b32_e32 v91, 0, v32, vcc
	v_mul_f32_e32 v32, 0x3e000000, v33
	v_mul_f32_e32 v32, 0x3fb8aa3b, v32
	v_exp_f32_e32 v32, v32
	v_add_u32_e32 v33, s19, v89
	v_cmp_le_i32_e32 vcc, v33, v88
	v_add_u32_e32 v33, s19, v33
	v_add_f32_e32 v90, v90, v91
	v_cndmask_b32_e32 v92, 0, v32, vcc
	v_mul_f32_e32 v32, 0x3e000000, v34
	v_mul_f32_e32 v32, 0x3fb8aa3b, v32
	v_exp_f32_e32 v32, v32
	v_cmp_le_i32_e32 vcc, v33, v88
	v_add_u32_e32 v33, s19, v33
	v_add_f32_e32 v90, v92, v90
	v_cndmask_b32_e32 v93, 0, v32, vcc
	v_mul_f32_e32 v32, 0x3e000000, v35
	v_mul_f32_e32 v32, 0x3fb8aa3b, v32
	v_exp_f32_e32 v32, v32
	v_cmp_le_i32_e32 vcc, v33, v88
	v_add_u32_e32 v33, s8, v33
	v_add_f32_e32 v90, v93, v90
	v_cndmask_b32_e32 v94, 0, v32, vcc
	v_mul_f32_e32 v32, 0x3e000000, v36
	v_mul_f32_e32 v32, 0x3fb8aa3b, v32
	v_exp_f32_e32 v32, v32
	v_cmp_le_i32_e32 vcc, v33, v88
	v_add_u32_e32 v33, s19, v33
	v_add_f32_e32 v90, v94, v90
	v_cndmask_b32_e32 v95, 0, v32, vcc
	v_mul_f32_e32 v32, 0x3e000000, v37
	v_mul_f32_e32 v32, 0x3fb8aa3b, v32
	v_exp_f32_e32 v32, v32
	v_cmp_le_i32_e32 vcc, v33, v88
	v_add_u32_e32 v33, s19, v33
	v_add_f32_e32 v90, v95, v90
	v_cndmask_b32_e32 v96, 0, v32, vcc
	v_mul_f32_e32 v32, 0x3e000000, v38
	v_mul_f32_e32 v32, 0x3fb8aa3b, v32
	v_exp_f32_e32 v32, v32
	v_cmp_le_i32_e32 vcc, v33, v88
	v_add_u32_e32 v33, s19, v33
	v_add_f32_e32 v90, v96, v90
	v_cndmask_b32_e32 v97, 0, v32, vcc
	v_mul_f32_e32 v32, 0x3e000000, v39
	v_mul_f32_e32 v32, 0x3fb8aa3b, v32
	v_exp_f32_e32 v32, v32
	v_cmp_le_i32_e32 vcc, v33, v88
	v_add_u32_e32 v33, s8, v33
	v_add_f32_e32 v90, v97, v90
	v_cndmask_b32_e32 v98, 0, v32, vcc
	v_mul_f32_e32 v32, 0x3e000000, v40
	v_mul_f32_e32 v32, 0x3fb8aa3b, v32
	v_exp_f32_e32 v32, v32
	v_cmp_le_i32_e32 vcc, v33, v88
	v_add_u32_e32 v33, s19, v33
	v_add_f32_e32 v90, v98, v90
	v_cndmask_b32_e32 v40, 0, v32, vcc
	v_mul_f32_e32 v32, 0x3e000000, v41
	v_mul_f32_e32 v32, 0x3fb8aa3b, v32
	v_exp_f32_e32 v32, v32
	v_cmp_le_i32_e32 vcc, v33, v88
	v_add_u32_e32 v33, s19, v33
	v_cvt_pk_bf16_f32 v34, v95, v96
	v_cvt_pk_bf16_f32 v35, v97, v98
	s_nop 0
	v_cndmask_b32_e32 v41, 0, v32, vcc
	v_mul_f32_e32 v32, 0x3e000000, v42
	v_mul_f32_e32 v32, 0x3fb8aa3b, v32
	v_exp_f32_e32 v32, v32
	v_cmp_le_i32_e32 vcc, v33, v88
	v_add_u32_e32 v33, s19, v33
	v_cvt_pk_bf16_f32 v36, v40, v41
	v_add_f32_e32 v40, v40, v90
	v_cndmask_b32_e32 v42, 0, v32, vcc
	v_mul_f32_e32 v32, 0x3e000000, v43
	v_mul_f32_e32 v32, 0x3fb8aa3b, v32
	v_exp_f32_e32 v32, v32
	v_cmp_le_i32_e32 vcc, v33, v88
	v_add_u32_e32 v33, s8, v33
	v_add_f32_e32 v40, v41, v40
	v_cndmask_b32_e32 v43, 0, v32, vcc
	v_mul_f32_e32 v32, 0x3e000000, v44
	v_mul_f32_e32 v32, 0x3fb8aa3b, v32
	v_exp_f32_e32 v32, v32
	v_cmp_le_i32_e32 vcc, v33, v88
	v_add_u32_e32 v33, s19, v33
	v_add_f32_e32 v40, v42, v40
	v_cndmask_b32_e32 v44, 0, v32, vcc
	v_mul_f32_e32 v32, 0x3e000000, v45
	v_mul_f32_e32 v32, 0x3fb8aa3b, v32
	v_exp_f32_e32 v32, v32
	v_cmp_le_i32_e32 vcc, v33, v88
	v_add_u32_e32 v33, s19, v33
	v_add_f32_e32 v40, v43, v40
	v_cndmask_b32_e32 v45, 0, v32, vcc
	v_mul_f32_e32 v32, 0x3e000000, v46
	v_mul_f32_e32 v32, 0x3fb8aa3b, v32
	v_exp_f32_e32 v32, v32
	v_cmp_le_i32_e32 vcc, v33, v88
	v_add_f32_e32 v40, v44, v40
	v_add_f32_e32 v40, v45, v40
	v_cndmask_b32_e32 v46, 0, v32, vcc
	v_cvt_pk_bf16_f32 v37, v42, v43
	v_cvt_pk_bf16_f32 v38, v44, v45
	v_add_f32_e32 v44, v46, v40
	ds_read2_b64 v[40:43], v87 offset0:16 offset1:18
	v_mul_f32_e32 v32, 0x3e000000, v47
	v_mul_f32_e32 v32, 0x3fb8aa3b, v32
	v_exp_f32_e32 v32, v32
	v_add_u32_e32 v89, s19, v33
	v_cmp_le_i32_e32 vcc, v89, v88
	v_cvt_pk_bf16_f32 v33, v93, v94
	v_add_u32_e32 v89, s8, v89
	s_nop 0
	v_cndmask_b32_e32 v47, 0, v32, vcc
	v_cvt_pk_bf16_f32 v32, v91, v92
	v_cvt_pk_bf16_f32 v39, v46, v47
	ds_read_b128 v[92:95], v84 offset:13856
	s_waitcnt lgkmcnt(1)
	v_mfma_f32_32x32x16_bf16 v[16:31], v[40:43], v[32:35], v[16:31]
	ds_read2_b64 v[40:43], v87 offset0:20 offset1:22
	v_add_f32_e32 v90, v47, v44
	v_cmp_le_i32_e32 vcc, v89, v88
	s_waitcnt lgkmcnt(0)
	v_mfma_f32_32x32x16_bf16 v[16:31], v[40:43], v[36:39], v[16:31]
	ds_read2_b64 v[40:43], v86 offset0:80 offset1:82
	s_waitcnt lgkmcnt(0)
	v_mfma_f32_32x32x16_bf16 v[0:15], v[40:43], v[32:35], v[0:15]
	ds_read2_b64 v[32:35], v86 offset0:84 offset1:86
	s_waitcnt lgkmcnt(0)
	v_mfma_f32_32x32x16_bf16 v[0:15], v[32:35], v[36:39], v[0:15]
	ds_read_b128 v[32:35], v84 offset:13824
	s_waitcnt lgkmcnt(0)
	v_mfma_f32_32x32x16_bf16 v[32:47], v[32:35], v[56:59], 0
	v_mfma_f32_32x32x16_bf16 v[32:47], v[92:95], v[48:51], v[32:47]
	ds_read_b128 v[92:95], v84 offset:13888
	s_waitcnt lgkmcnt(0)
; __device__ __forceinline__ unsigned pack2(float a, float b) { unsigned r; asm("v_cvt_pk_bf16_f32 %0, %1, %2" : "=v"(r) : "v"(a), "v"(b)); return r; }
; __device__ __forceinline__ void attn_item(const Params& p, int layer, bool isctx, int item, unsigned char* smem) {
;     ...
; #pragma unroll
;     for (int k4 = 0; k4 < 4; k4++) {
;       f32x16 st;
; #pragma unroll
;       for (int r = 0; r < 16; r++) st[r] = 0.f;
; #pragma unroll
;       for (int ks = 0; ks < 4; ks++) {
;         bf16x8 kf = *(const bf16x8*)(Ks + (k4 * 32 + (lane & 31)) * 72 + ks * 16 + hh * 8);
;         st = __builtin_amdgcn_mfma_f32_32x32x16_bf16(kf, qf[ks], st, 0, 0, 0);
;       }
;       float pe[16];
; #pragma unroll
;       for (int r = 0; r < 16; r++) {
;         int kl = k4 * 32 + (r & 3) + 8 * (r >> 2) + 4 * hh;
;         float e = __expf(st[r] * 0.125f);
;         bool valid = (mtype * kl) <= mq;
;         e = valid ? e : 0.f;
;         pe[r] = e; rsum += e;
;       }
;       bf16x8 pb[2];
; #pragma unroll
;       for (int s = 0; s < 2; s++) {
;         union { bf16x8 v; unsigned w[4]; } cv;
; #pragma unroll
;         for (int q = 0; q < 4; q++) cv.w[q] = pack2(pe[8 * s + 2 * q], pe[8 * s + 2 * q + 1]);
;         pb[s] = cv.v;
;       }
; #pragma unroll
;       for (int mt = 0; mt < 2; mt++)
; #pragma unroll
;         for (int s = 0; s < 2; s++) {
;           const u16* vp = Vt + (mt * 32 + (lane & 31)) * 136 + k4 * 32 + 16 * s + 4 * hh;
;           union { bf16x8 v; uint2 h2[2]; } av;
;           av.h2[0] = *(const uint2*)vp;
;           av.h2[1] = *(const uint2*)(vp + 8);
;           oacc[mt] = __builtin_amdgcn_mfma_f32_32x32x16_bf16(av.v, pb[s], oacc[mt], 0, 0, 0);
;         }
;     }
	v_mfma_f32_32x32x16_bf16 v[32:47], v[92:95], v[52:55], v[32:47]
	ds_read_b128 v[92:95], v84 offset:13920
	s_waitcnt lgkmcnt(0)
	v_mfma_f32_32x32x16_bf16 v[32:47], v[92:95], v[60:63], v[32:47]
	s_nop 11
	v_mul_f32_e32 v32, 0x3e000000, v32
	v_mul_f32_e32 v32, 0x3fb8aa3b, v32
	v_exp_f32_e32 v32, v32
	s_nop 0
	v_cndmask_b32_e32 v91, 0, v32, vcc
	v_mul_f32_e32 v32, 0x3e000000, v33
	v_mul_f32_e32 v32, 0x3fb8aa3b, v32
	v_exp_f32_e32 v32, v32
	v_add_u32_e32 v33, s19, v89
	v_cmp_le_i32_e32 vcc, v33, v88
	v_add_u32_e32 v33, s19, v33
	s_nop 0
	v_cndmask_b32_e32 v89, 0, v32, vcc
	v_mul_f32_e32 v32, 0x3e000000, v34
	v_mul_f32_e32 v32, 0x3fb8aa3b, v32
	v_exp_f32_e32 v32, v32
	v_cmp_le_i32_e32 vcc, v33, v88
	v_add_u32_e32 v33, s19, v33
	s_nop 0
	v_cndmask_b32_e32 v92, 0, v32, vcc
	v_mul_f32_e32 v32, 0x3e000000, v35
	v_mul_f32_e32 v32, 0x3fb8aa3b, v32
	v_exp_f32_e32 v32, v32
	v_cmp_le_i32_e32 vcc, v33, v88
	v_add_u32_e32 v33, s8, v33
	s_nop 0
	v_cndmask_b32_e32 v93, 0, v32, vcc
	v_mul_f32_e32 v32, 0x3e000000, v36
	v_mul_f32_e32 v32, 0x3fb8aa3b, v32
	v_exp_f32_e32 v32, v32
	v_cmp_le_i32_e32 vcc, v33, v88
	v_add_u32_e32 v33, s19, v33
	v_cvt_pk_bf16_f32 v36, v91, v89
	s_nop 0
	v_cndmask_b32_e32 v94, 0, v32, vcc
	v_mul_f32_e32 v32, 0x3e000000, v37
	v_mul_f32_e32 v32, 0x3fb8aa3b, v32
	v_exp_f32_e32 v32, v32
	v_cmp_le_i32_e32 vcc, v33, v88
	v_add_u32_e32 v33, s19, v33
	v_cvt_pk_bf16_f32 v37, v92, v93
	s_nop 0
	v_cndmask_b32_e32 v95, 0, v32, vcc
	v_mul_f32_e32 v32, 0x3e000000, v38
	v_mul_f32_e32 v32, 0x3fb8aa3b, v32
	v_exp_f32_e32 v32, v32
	v_cmp_le_i32_e32 vcc, v33, v88
	v_add_u32_e32 v33, s19, v33
	v_cvt_pk_bf16_f32 v38, v94, v95
	s_nop 0
	v_cndmask_b32_e32 v96, 0, v32, vcc
	v_mul_f32_e32 v32, 0x3e000000, v39
	v_mul_f32_e32 v32, 0x3fb8aa3b, v32
	v_exp_f32_e32 v32, v32
	v_cmp_le_i32_e32 vcc, v33, v88
	v_add_u32_e32 v33, s8, v33
	s_nop 0
	v_cndmask_b32_e32 v97, 0, v32, vcc
	v_mul_f32_e32 v32, 0x3e000000, v40
	v_mul_f32_e32 v32, 0x3fb8aa3b, v32
	v_exp_f32_e32 v32, v32
	v_cmp_le_i32_e32 vcc, v33, v88
	v_add_u32_e32 v33, s19, v33
	v_cvt_pk_bf16_f32 v39, v96, v97
	s_nop 0
	v_cndmask_b32_e32 v40, 0, v32, vcc
	v_mul_f32_e32 v32, 0x3e000000, v41
	v_mul_f32_e32 v32, 0x3fb8aa3b, v32
	v_exp_f32_e32 v32, v32
	v_cmp_le_i32_e32 vcc, v33, v88
	v_add_u32_e32 v33, s19, v33
	s_nop 0
	v_cndmask_b32_e32 v41, 0, v32, vcc
	v_mul_f32_e32 v32, 0x3e000000, v42
	v_mul_f32_e32 v32, 0x3fb8aa3b, v32
	v_exp_f32_e32 v32, v32
	v_cmp_le_i32_e32 vcc, v33, v88
	v_add_u32_e32 v33, s19, v33
	s_nop 0
	v_cndmask_b32_e32 v42, 0, v32, vcc
	v_mul_f32_e32 v32, 0x3e000000, v43
	v_mul_f32_e32 v32, 0x3fb8aa3b, v32
	v_exp_f32_e32 v32, v32
	v_cmp_le_i32_e32 vcc, v33, v88
	v_add_u32_e32 v33, s8, v33
	s_nop 0
	v_cndmask_b32_e32 v43, 0, v32, vcc
	v_mul_f32_e32 v32, 0x3e000000, v44
	v_mul_f32_e32 v32, 0x3fb8aa3b, v32
	v_exp_f32_e32 v32, v32
	v_cmp_le_i32_e32 vcc, v33, v88
	v_add_u32_e32 v33, s19, v33
	s_nop 0
	v_cndmask_b32_e32 v44, 0, v32, vcc
	v_mul_f32_e32 v32, 0x3e000000, v45
	v_mul_f32_e32 v32, 0x3fb8aa3b, v32
	v_exp_f32_e32 v32, v32
	v_cmp_le_i32_e32 vcc, v33, v88
	v_add_u32_e32 v33, s19, v33
	s_nop 0
	v_cndmask_b32_e32 v45, 0, v32, vcc
	v_mul_f32_e32 v32, 0x3e000000, v46
	v_mul_f32_e32 v32, 0x3fb8aa3b, v32
	v_exp_f32_e32 v32, v32
	v_cmp_le_i32_e32 vcc, v33, v88
	v_add_u32_e32 v33, s19, v33
	v_cvt_pk_bf16_f32 v34, v44, v45
	s_nop 0
	v_cndmask_b32_e32 v46, 0, v32, vcc
	v_cmp_le_i32_e32 vcc, v33, v88
	v_add_f32_e32 v88, v90, v91
	v_add_f32_e32 v88, v89, v88
	v_mul_f32_e32 v32, 0x3e000000, v47
	v_add_f32_e32 v88, v92, v88
	v_mul_f32_e32 v32, 0x3fb8aa3b, v32
	v_add_f32_e32 v88, v93, v88
	v_exp_f32_e32 v32, v32
	v_add_f32_e32 v88, v94, v88
	v_add_f32_e32 v88, v95, v88
	v_add_f32_e32 v88, v96, v88
	v_add_f32_e32 v88, v97, v88
	v_cndmask_b32_e32 v47, 0, v32, vcc
	v_cvt_pk_bf16_f32 v32, v40, v41
	v_add_f32_e32 v40, v40, v88
	v_add_f32_e32 v40, v41, v40
	v_add_f32_e32 v40, v42, v40
	v_add_f32_e32 v40, v43, v40
	v_add_f32_e32 v40, v44, v40
	v_add_f32_e32 v40, v45, v40
	v_cvt_pk_bf16_f32 v33, v42, v43
	v_add_f32_e32 v44, v46, v40
	ds_read2_b64 v[40:43], v87 offset0:24 offset1:26
	s_waitcnt lgkmcnt(0)
	v_mfma_f32_32x32x16_bf16 v[16:31], v[40:43], v[36:39], v[16:31]
	ds_read2_b64 v[40:43], v87 offset0:28 offset1:30
	v_cvt_pk_bf16_f32 v35, v46, v47
	s_waitcnt lgkmcnt(0)
	v_mfma_f32_32x32x16_bf16 v[16:31], v[40:43], v[32:35], v[16:31]
	ds_read2_b64 v[40:43], v86 offset0:88 offset1:90
	s_waitcnt lgkmcnt(0)
	v_mfma_f32_32x32x16_bf16 v[0:15], v[40:43], v[36:39], v[0:15]
	ds_read2_b64 v[36:39], v86 offset0:92 offset1:94
	v_add_f32_e32 v86, v47, v44
	s_waitcnt lgkmcnt(0)
	v_mfma_f32_32x32x16_bf16 v[0:15], v[36:39], v[32:35], v[0:15]
	s_add_i32 s15, s15, 1
	s_addk_i32 s17, 0x80
	s_cmp_lg_u32 s18, 4
	s_cbranch_scc0 .LBB0_482
